# ssm pass 3 scan: in-loop counted waits no longer cover the previous block's stores
# baseline (speedup 1.0000x reference)
; #define LAS __attribute__((address_space(3)))
; __device__ __forceinline__ void ssm_pass3h(CArgs* ap, const float* COEF, int l, const bf16_t* PROJ, const float* SST, bf16_t* YS, LAS unsigned char* wlds, int unit, int lane) {
;     ...
;     const size_t row0 = (size_t)(b * SEQ + c * 128);
;     const bf16_t* up = PROJ + row0 * INW + 2560 + g * 16;
;     LAS float* Hf = (LAS float*)wlds;
;     u32x4 wn[8];
; #pragma unroll
;     for (int tt = 0; tt < 4; ++tt) { wn[2 * tt] = ((const u32x4*)(up + (size_t)tt * INW))[0]; wn[2 * tt + 1] = ((const u32x4*)(up + (size_t)tt * INW))[1]; }
.LBB0_148:
	s_lshl_b32 s0, s9, 2
	s_and_b32 s0, s0, 0xffffe000
	s_lshl_b32 s1, s3, 7
	s_or_b32 s0, s0, s1
	s_ashr_i32 s1, s0, 31
	s_mul_i32 s10, s0, 0x4800
	s_mul_hi_i32 s3, s0, 0x4800
	s_add_u32 s10, s68, s10
	s_addc_u32 s3, s69, s3
	s_lshl_b32 s78, s2, 1
	s_add_u32 s10, s10, s78
	s_addc_u32 s11, s3, 0
	s_add_u32 s2, s10, 0x1400
	s_addc_u32 s3, s11, 0
	s_add_u32 s12, s10, 0x5c00
	v_mov_b32_e32 v0, 0x5000
	v_and_b32_e32 v224, 3, v166
	v_mul_u32_u24_e32 v224, 0x4800, v224
	v_mov_b32_e32 v208, v101
	v_mov_b32_e32 v209, v103
	v_mov_b32_e32 v210, v102
	v_mov_b32_e32 v211, v104
	v_mov_b32_e32 v212, v105
	v_mov_b32_e32 v213, v107
	v_mov_b32_e32 v214, v106
	v_mov_b32_e32 v215, v108
	v_mov_b32_e32 v216, v109
	v_mov_b32_e32 v217, v111
	v_mov_b32_e32 v218, v110
	v_mov_b32_e32 v219, v112
	v_mov_b32_e32 v220, v113
	v_mov_b32_e32 v221, v115
	v_mov_b32_e32 v222, v114
	v_mov_b32_e32 v223, v116
	global_load_dwordx4 v[20:23], v224, s[2:3] offset:16
	global_load_dwordx4 v[24:27], v224, s[2:3]
	s_add_u32 s12, s2, 0x12000
	s_addc_u32 s13, s3, 0
	global_load_dwordx4 v[28:31], v224, s[12:13] offset:16
	global_load_dwordx4 v[32:35], v224, s[12:13]
	s_add_u32 s12, s2, 0x24000
	s_addc_u32 s13, s3, 0
	global_load_dwordx4 v[36:39], v224, s[12:13] offset:16
	global_load_dwordx4 v[40:43], v224, s[12:13]
	s_add_u32 s12, s2, 0x36000
	s_addc_u32 s13, s3, 0
	global_load_dwordx4 v[44:47], v224, s[12:13] offset:16
	global_load_dwordx4 v[48:51], v224, s[12:13]
	v_lshl_add_u64 v[92:93], v[80:81], 0, s[78:79]
	v_pk_mov_b32 v[94:95], v[2:3], v[2:3] op_sel:[1,0]
	s_mov_b32 s10, 0
	s_waitcnt vmcnt(12)
	v_xor_b32_e32 v89, 0x80000000, v64
	v_xor_b32_e32 v117, 0x80000000, v65
	v_xor_b32_e32 v118, 0x80000000, v66
	v_xor_b32_e32 v119, 0x80000000, v67
	s_waitcnt vmcnt(11)
	v_xor_b32_e32 v120, 0x80000000, v60
	v_xor_b32_e32 v121, 0x80000000, v61
	v_xor_b32_e32 v122, 0x80000000, v62
	v_xor_b32_e32 v123, 0x80000000, v63
	s_waitcnt vmcnt(10)
	v_xor_b32_e32 v124, 0x80000000, v56
	v_xor_b32_e32 v125, 0x80000000, v57
	v_xor_b32_e32 v126, 0x80000000, v58
	v_xor_b32_e32 v127, 0x80000000, v59
	s_waitcnt vmcnt(9)
	v_xor_b32_e32 v128, 0x80000000, v52
	v_xor_b32_e32 v129, 0x80000000, v53
	v_xor_b32_e32 v130, 0x80000000, v54
	v_xor_b32_e32 v131, 0x80000000, v55
	s_mov_b32 s11, 0
	s_waitcnt vmcnt(0)

; __device__ __forceinline__ void ssm_pass3h(CArgs* ap, const float* COEF, int l, const bf16_t* PROJ, const float* SST, bf16_t* YS, LAS unsigned char* wlds, int unit, int lane) {
;     ...
;         for (int q = 0; q < 4; ++q) {
;             const int t = 16 * blk + 4 * q;
;             u32x4 wc[8];
; #pragma unroll
;             for (int j = 0; j < 8; ++j) wc[j] = wn[j];
;             const int tn = (t + 4 < 128) ? t + 4 : t;
; #pragma unroll
;             for (int tt = 0; tt < 4; ++tt) { wn[2 * tt] = ((const u32x4*)(up + (size_t)(tn + tt) * INW))[0]; wn[2 * tt + 1] = ((const u32x4*)(up + (size_t)(tn + tt) * INW))[1]; }
; #pragma unroll
;             for (int tt = 0; tt < 4; ++tt) {
;                 const u32x4 w0 = wc[2 * tt], w1 = wc[2 * tt + 1];
;                 const unsigned u2[8] = {w0.x, w0.y, w0.z, w0.w, w1.x, w1.y, w1.z, w1.w};
;                 float br_ = 0.f, bi_ = 0.f;
; #pragma unroll
;                 for (int k = 0; k < 8; ++k) { br_ = __builtin_amdgcn_fdot2_f32_bf16(__builtin_bit_cast(bf16x2v, bbr2[k]), __builtin_bit_cast(bf16x2v, u2[k]), br_, false);
;                                                bi_ = __builtin_amdgcn_fdot2_f32_bf16(__builtin_bit_cast(bf16x2v, bbi2[k]), __builtin_bit_cast(bf16x2v, u2[k]), bi_, false); }
;                 const float nr = abr * hr - abi * hi + br_, ni = abr * hi + abi * hr + bi_; hr = nr; hi = ni;
;                 Hf[(4 * q + tt) * 132 + lane] = hr; Hf[(4 * q + tt) * 132 + 64 + lane] = hi;
;             }
.LBB0_150:
	s_add_i32 s13, s14, 4
	s_add_i32 s78, s14, 16
	s_cmpk_lt_u32 s14, 0x70
	s_cselect_b32 s78, s78, s14
	s_mul_i32 s78, s78, 0x2400
	s_lshl_b64 s[14:15], s[78:79], 1
	s_add_u32 s14, s2, s14
	s_addc_u32 s15, s3, s15
	s_waitcnt vmcnt(14)
	v_mfma_f32_4x4x4_16b_bf16 v[144:147], v[24:25], v[208:209], 0
	v_mfma_f32_4x4x4_16b_bf16 v[148:151], v[24:25], v[210:211], 0
	s_nop 0
	v_mfma_f32_4x4x4_16b_bf16 v[144:147], v[26:27], v[212:213], v[144:147]
	v_mfma_f32_4x4x4_16b_bf16 v[148:151], v[26:27], v[214:215], v[148:151]
	s_nop 0
	v_mfma_f32_4x4x4_16b_bf16 v[144:147], v[20:21], v[216:217], v[144:147]
	v_mfma_f32_4x4x4_16b_bf16 v[148:151], v[20:21], v[218:219], v[148:151]
	s_nop 0
	v_mfma_f32_4x4x4_16b_bf16 v[144:147], v[22:23], v[220:221], v[144:147]
	v_mfma_f32_4x4x4_16b_bf16 v[148:151], v[22:23], v[222:223], v[148:151]
	global_load_dwordx4 v[20:23], v224, s[14:15] offset:16
	global_load_dwordx4 v[24:27], v224, s[14:15]
	v_add_u32_e32 v97, s12, v99
	v_add_u32_e32 v184, 32, v97
	v_add_u32_e32 v185, 48, v97
	v_pk_mul_f32 v[152:153], v[2:3], v[90:91]
	v_pk_mul_f32 v[154:155], v[94:95], v[90:91]
	v_sub_f32_e32 v152, v152, v153
	v_add_f32_e32 v153, v154, v155
	v_add_f32_e32 v90, v144, v152
	v_add_f32_e32 v91, v148, v153
	ds_write2st64_b32 v97, v90, v91 offset1:1
	v_pk_mul_f32 v[152:153], v[2:3], v[90:91]
	v_pk_mul_f32 v[154:155], v[94:95], v[90:91]
	v_sub_f32_e32 v152, v152, v153
	v_add_f32_e32 v153, v154, v155
	v_add_f32_e32 v90, v145, v152
	v_add_f32_e32 v91, v149, v153
	ds_write2_b32 v97, v90, v91 offset0:132 offset1:196
	v_pk_mul_f32 v[152:153], v[2:3], v[90:91]
	v_pk_mul_f32 v[154:155], v[94:95], v[90:91]
	v_sub_f32_e32 v152, v152, v153
	v_add_f32_e32 v153, v154, v155
	v_add_f32_e32 v90, v146, v152
	v_add_f32_e32 v91, v150, v153
	ds_write2st64_b32 v184, v90, v91 offset0:4 offset1:5
	v_pk_mul_f32 v[152:153], v[2:3], v[90:91]
	v_pk_mul_f32 v[154:155], v[94:95], v[90:91]
	v_sub_f32_e32 v152, v152, v153
	v_add_f32_e32 v153, v154, v155
	v_add_f32_e32 v90, v147, v152
	v_add_f32_e32 v91, v151, v153
	ds_write2st64_b32 v185, v90, v91 offset0:6 offset1:7
	s_addk_i32 s12, 0x840
	s_mov_b32 s14, s13
	s_add_i32 s13, s14, 4
	s_add_i32 s78, s14, 16
	s_cmpk_lt_u32 s14, 0x70
	s_cselect_b32 s78, s78, s14
	s_mul_i32 s78, s78, 0x2400
	s_lshl_b64 s[14:15], s[78:79], 1
	s_add_u32 s14, s2, s14
	s_addc_u32 s15, s3, s15
	s_waitcnt vmcnt(14)
	v_mfma_f32_4x4x4_16b_bf16 v[144:147], v[32:33], v[208:209], 0
	v_mfma_f32_4x4x4_16b_bf16 v[148:151], v[32:33], v[210:211], 0
	s_nop 0
	v_mfma_f32_4x4x4_16b_bf16 v[144:147], v[34:35], v[212:213], v[144:147]
	v_mfma_f32_4x4x4_16b_bf16 v[148:151], v[34:35], v[214:215], v[148:151]
	s_nop 0
	v_mfma_f32_4x4x4_16b_bf16 v[144:147], v[28:29], v[216:217], v[144:147]
	v_mfma_f32_4x4x4_16b_bf16 v[148:151], v[28:29], v[218:219], v[148:151]
	s_nop 0
	v_mfma_f32_4x4x4_16b_bf16 v[144:147], v[30:31], v[220:221], v[144:147]
	v_mfma_f32_4x4x4_16b_bf16 v[148:151], v[30:31], v[222:223], v[148:151]
	global_load_dwordx4 v[28:31], v224, s[14:15] offset:16
	global_load_dwordx4 v[32:35], v224, s[14:15]
	v_add_u32_e32 v97, s12, v99
	v_add_u32_e32 v184, 32, v97
	v_add_u32_e32 v185, 48, v97
	v_pk_mul_f32 v[152:153], v[2:3], v[90:91]
	v_pk_mul_f32 v[154:155], v[94:95], v[90:91]
	v_sub_f32_e32 v152, v152, v153
	v_add_f32_e32 v153, v154, v155
	v_add_f32_e32 v90, v144, v152
	v_add_f32_e32 v91, v148, v153
	ds_write2st64_b32 v97, v90, v91 offset1:1
	v_pk_mul_f32 v[152:153], v[2:3], v[90:91]
	v_pk_mul_f32 v[154:155], v[94:95], v[90:91]
	v_sub_f32_e32 v152, v152, v153
	v_add_f32_e32 v153, v154, v155
	v_add_f32_e32 v90, v145, v152
	v_add_f32_e32 v91, v149, v153
	ds_write2_b32 v97, v90, v91 offset0:132 offset1:196
	v_pk_mul_f32 v[152:153], v[2:3], v[90:91]
	v_pk_mul_f32 v[154:155], v[94:95], v[90:91]
	v_sub_f32_e32 v152, v152, v153
	v_add_f32_e32 v153, v154, v155
	v_add_f32_e32 v90, v146, v152
	v_add_f32_e32 v91, v150, v153
	ds_write2st64_b32 v184, v90, v91 offset0:4 offset1:5
	v_pk_mul_f32 v[152:153], v[2:3], v[90:91]
	v_pk_mul_f32 v[154:155], v[94:95], v[90:91]
	v_sub_f32_e32 v152, v152, v153
	v_add_f32_e32 v153, v154, v155
	v_add_f32_e32 v90, v147, v152
	v_add_f32_e32 v91, v151, v153
	ds_write2st64_b32 v185, v90, v91 offset0:6 offset1:7
	s_addk_i32 s12, 0x840
	s_mov_b32 s14, s13
	s_add_i32 s13, s14, 4
	s_add_i32 s78, s14, 16
	s_cmpk_lt_u32 s14, 0x70
	s_cselect_b32 s78, s78, s14
	s_mul_i32 s78, s78, 0x2400
	s_lshl_b64 s[14:15], s[78:79], 1
	s_add_u32 s14, s2, s14
	s_addc_u32 s15, s3, s15
	s_waitcnt vmcnt(14)
	v_mfma_f32_4x4x4_16b_bf16 v[144:147], v[40:41], v[208:209], 0
	v_mfma_f32_4x4x4_16b_bf16 v[148:151], v[40:41], v[210:211], 0
	s_nop 0
	v_mfma_f32_4x4x4_16b_bf16 v[144:147], v[42:43], v[212:213], v[144:147]
	v_mfma_f32_4x4x4_16b_bf16 v[148:151], v[42:43], v[214:215], v[148:151]
	s_nop 0
	v_mfma_f32_4x4x4_16b_bf16 v[144:147], v[36:37], v[216:217], v[144:147]
	v_mfma_f32_4x4x4_16b_bf16 v[148:151], v[36:37], v[218:219], v[148:151]
	s_nop 0
	v_mfma_f32_4x4x4_16b_bf16 v[144:147], v[38:39], v[220:221], v[144:147]
	v_mfma_f32_4x4x4_16b_bf16 v[148:151], v[38:39], v[222:223], v[148:151]
	global_load_dwordx4 v[36:39], v224, s[14:15] offset:16
	global_load_dwordx4 v[40:43], v224, s[14:15]
	v_add_u32_e32 v97, s12, v99
	v_add_u32_e32 v184, 32, v97
	v_add_u32_e32 v185, 48, v97
	v_pk_mul_f32 v[152:153], v[2:3], v[90:91]
	v_pk_mul_f32 v[154:155], v[94:95], v[90:91]
	v_sub_f32_e32 v152, v152, v153
	v_add_f32_e32 v153, v154, v155
	v_add_f32_e32 v90, v144, v152
	v_add_f32_e32 v91, v148, v153
	ds_write2st64_b32 v97, v90, v91 offset1:1
	v_pk_mul_f32 v[152:153], v[2:3], v[90:91]
	v_pk_mul_f32 v[154:155], v[94:95], v[90:91]
	v_sub_f32_e32 v152, v152, v153
	v_add_f32_e32 v153, v154, v155
	v_add_f32_e32 v90, v145, v152
	v_add_f32_e32 v91, v149, v153
	ds_write2_b32 v97, v90, v91 offset0:132 offset1:196
	v_pk_mul_f32 v[152:153], v[2:3], v[90:91]
	v_pk_mul_f32 v[154:155], v[94:95], v[90:91]
	v_sub_f32_e32 v152, v152, v153
	v_add_f32_e32 v153, v154, v155
	v_add_f32_e32 v90, v146, v152
	v_add_f32_e32 v91, v150, v153
	ds_write2st64_b32 v184, v90, v91 offset0:4 offset1:5
	v_pk_mul_f32 v[152:153], v[2:3], v[90:91]
	v_pk_mul_f32 v[154:155], v[94:95], v[90:91]
	v_sub_f32_e32 v152, v152, v153
	v_add_f32_e32 v153, v154, v155
	v_add_f32_e32 v90, v147, v152
	v_add_f32_e32 v91, v151, v153
	ds_write2st64_b32 v185, v90, v91 offset0:6 offset1:7
	s_addk_i32 s12, 0x840
	s_mov_b32 s14, s13
	s_add_i32 s13, s14, 4
	s_add_i32 s78, s14, 16
	s_cmpk_lt_u32 s14, 0x70
	s_cselect_b32 s78, s78, s14
	s_mul_i32 s78, s78, 0x2400
	s_lshl_b64 s[14:15], s[78:79], 1
	s_add_u32 s14, s2, s14
	s_addc_u32 s15, s3, s15
	s_waitcnt vmcnt(14)
; __device__ __forceinline__ float gelu_t(float x) { const float p = __builtin_fmaf(x * x, -0.10294324f, -2.30220819f); return x * __builtin_amdgcn_rcpf(1.f + __builtin_amdgcn_exp2f(x * p)); }
; #define LAS __attribute__((address_space(3)))
; __device__ __forceinline__ unsigned f2bf(float f) { unsigned u = __builtin_bit_cast(unsigned, f); return (u + 0x7fffu + ((u >> 16) & 1u)) >> 16; }
; __device__ __forceinline__ void ssm_pass3h(CArgs* ap, const float* COEF, int l, const bf16_t* PROJ, const float* SST, bf16_t* YS, LAS unsigned char* wlds, int unit, int lane) {
;     ...
;             for (int tt = 0; tt < 4; ++tt) {
;                 const u32x4 w0 = wc[2 * tt], w1 = wc[2 * tt + 1];
;                 const unsigned u2[8] = {w0.x, w0.y, w0.z, w0.w, w1.x, w1.y, w1.z, w1.w};
;                 float br_ = 0.f, bi_ = 0.f;
; #pragma unroll
;                 for (int k = 0; k < 8; ++k) { br_ = __builtin_amdgcn_fdot2_f32_bf16(__builtin_bit_cast(bf16x2v, bbr2[k]), __builtin_bit_cast(bf16x2v, u2[k]), br_, false);
;                                                bi_ = __builtin_amdgcn_fdot2_f32_bf16(__builtin_bit_cast(bf16x2v, bbi2[k]), __builtin_bit_cast(bf16x2v, u2[k]), bi_, false); }
;                 const float nr = abr * hr - abi * hi + br_, ni = abr * hi + abi * hr + bi_; hr = nr; hi = ni;
;                 Hf[(4 * q + tt) * 132 + lane] = hr; Hf[(4 * q + tt) * 132 + 64 + lane] = hi;
;             }
;         }
;         asm volatile("s_waitcnt lgkmcnt(0)" ::: "memory");
;         f32x4 y = (f32x4){0.f, 0.f, 0.f, 0.f};
; #pragma unroll
;         for (int j = 0; j < 8; ++j) {
;             const f32x4 a4 = *(const LAS f32x4*)(Hf + fr * 132 + 16 * j + 4 * fq);
; #pragma unroll
;             for (int r = 0; r < 4; ++r) y = __builtin_amdgcn_mfma_f32_16x16x4f32(a4[r], cmB[4 * j + r], y, 0, 0, 0);
;         }
;         asm volatile("s_waitcnt lgkmcnt(0)" ::: "memory");
; #pragma unroll
;         for (int i = 0; i < 4; ++i) {
;             const size_t row = row0 + 16 * blk + 4 * fq + i;
;             YS[row * 512 + g * 16 + fr] = (bf16_t)f2bf(gelu_t(y[i] + dsk * __uint_as_float(((unsigned)uq[i]) << 16)));
;         }
	v_mfma_f32_4x4x4_16b_bf16 v[144:147], v[48:49], v[208:209], 0
	v_mfma_f32_4x4x4_16b_bf16 v[148:151], v[48:49], v[210:211], 0
	s_nop 0
	v_mfma_f32_4x4x4_16b_bf16 v[144:147], v[50:51], v[212:213], v[144:147]
	v_mfma_f32_4x4x4_16b_bf16 v[148:151], v[50:51], v[214:215], v[148:151]
	s_nop 0
	v_mfma_f32_4x4x4_16b_bf16 v[144:147], v[44:45], v[216:217], v[144:147]
	v_mfma_f32_4x4x4_16b_bf16 v[148:151], v[44:45], v[218:219], v[148:151]
	s_nop 0
	v_mfma_f32_4x4x4_16b_bf16 v[144:147], v[46:47], v[220:221], v[144:147]
	v_mfma_f32_4x4x4_16b_bf16 v[148:151], v[46:47], v[222:223], v[148:151]
	global_load_dwordx4 v[44:47], v224, s[14:15] offset:16
	global_load_dwordx4 v[48:51], v224, s[14:15]
	v_add_u32_e32 v97, s12, v99
	v_add_u32_e32 v184, 32, v97
	v_add_u32_e32 v185, 48, v97
	v_pk_mul_f32 v[152:153], v[2:3], v[90:91]
	v_pk_mul_f32 v[154:155], v[94:95], v[90:91]
	v_sub_f32_e32 v152, v152, v153
	v_add_f32_e32 v153, v154, v155
	v_add_f32_e32 v90, v144, v152
	v_add_f32_e32 v91, v148, v153
	ds_write2st64_b32 v97, v90, v91 offset1:1
	v_pk_mul_f32 v[152:153], v[2:3], v[90:91]
	v_pk_mul_f32 v[154:155], v[94:95], v[90:91]
	v_sub_f32_e32 v152, v152, v153
	v_add_f32_e32 v153, v154, v155
	v_add_f32_e32 v90, v145, v152
	v_add_f32_e32 v91, v149, v153
	ds_write2_b32 v97, v90, v91 offset0:132 offset1:196
	v_pk_mul_f32 v[152:153], v[2:3], v[90:91]
	v_pk_mul_f32 v[154:155], v[94:95], v[90:91]
	v_sub_f32_e32 v152, v152, v153
	v_add_f32_e32 v153, v154, v155
	v_add_f32_e32 v90, v146, v152
	v_add_f32_e32 v91, v150, v153
	ds_write2st64_b32 v184, v90, v91 offset0:4 offset1:5
	v_pk_mul_f32 v[152:153], v[2:3], v[90:91]
	v_pk_mul_f32 v[154:155], v[94:95], v[90:91]
	v_sub_f32_e32 v152, v152, v153
	v_add_f32_e32 v153, v154, v155
	v_add_f32_e32 v90, v147, v152
	v_add_f32_e32 v91, v151, v153
	ds_write2st64_b32 v185, v90, v91 offset0:6 offset1:7
	s_addk_i32 s12, 0x840
	s_mov_b32 s14, s13
	s_waitcnt lgkmcnt(0)
	ds_read_b128 v[144:147], v100
	ds_read_b128 v[148:151], v100 offset:64
	ds_read_b128 v[152:155], v100 offset:128
	ds_read_b128 v[168:171], v100 offset:192
	ds_read_b128 v[172:175], v100 offset:256
	ds_read_b128 v[176:179], v100 offset:320
	ds_read_b128 v[180:183], v100 offset:384
	ds_read_b128 v[184:187], v100 offset:448
	s_waitcnt vmcnt(11)
	v_lshlrev_b32_e32 v57, 16, v135
	v_mov_b32_e32 v97, v1
	v_or_b32_e32 v0, 1, v96
	v_or_b32_e32 v58, 2, v96
	v_mov_b32_e32 v59, v1
	v_or_b32_e32 v56, 3, v96
	s_add_i32 s11, s11, 1
	s_add_i32 s10, s10, 16
	s_cmp_eq_u32 s11, 8
	v_lshl_add_u64 v[60:61], v[96:97], 0, s[0:1]
	v_lshlrev_b64 v[60:61], 10, v[60:61]
	v_lshl_add_u64 v[60:61], v[92:93], 0, v[60:61]
	s_waitcnt lgkmcnt(6)
	v_mfma_f32_16x16x4_f32 v[52:55], v144, v4, 0
	v_mfma_f32_16x16x4_f32 v[188:191], v148, v8, 0
	v_mfma_f32_16x16x4_f32 v[52:55], v145, v5, v[52:55]
	v_mfma_f32_16x16x4_f32 v[188:191], v149, v9, v[188:191]
	v_mfma_f32_16x16x4_f32 v[52:55], v146, v6, v[52:55]
	v_mfma_f32_16x16x4_f32 v[188:191], v150, v10, v[188:191]
	v_mfma_f32_16x16x4_f32 v[52:55], v147, v7, v[52:55]
	v_mfma_f32_16x16x4_f32 v[188:191], v151, v11, v[188:191]
	s_waitcnt lgkmcnt(4)
	v_mfma_f32_16x16x4_f32 v[52:55], v152, v12, v[52:55]
	v_mfma_f32_16x16x4_f32 v[188:191], v168, v16, v[188:191]
	v_mfma_f32_16x16x4_f32 v[52:55], v153, v13, v[52:55]
	v_mfma_f32_16x16x4_f32 v[188:191], v169, v17, v[188:191]
	v_mfma_f32_16x16x4_f32 v[52:55], v154, v14, v[52:55]
	v_mfma_f32_16x16x4_f32 v[188:191], v170, v18, v[188:191]
	v_mfma_f32_16x16x4_f32 v[52:55], v155, v15, v[52:55]
	v_mfma_f32_16x16x4_f32 v[188:191], v171, v19, v[188:191]
	s_waitcnt lgkmcnt(2)
	v_mfma_f32_16x16x4_f32 v[52:55], v172, v89, v[52:55]
	v_mfma_f32_16x16x4_f32 v[188:191], v176, v120, v[188:191]
	v_mfma_f32_16x16x4_f32 v[52:55], v173, v117, v[52:55]
	v_mfma_f32_16x16x4_f32 v[188:191], v177, v121, v[188:191]
	v_mfma_f32_16x16x4_f32 v[52:55], v174, v118, v[52:55]
	v_mfma_f32_16x16x4_f32 v[188:191], v178, v122, v[188:191]
	v_mfma_f32_16x16x4_f32 v[52:55], v175, v119, v[52:55]
	v_mfma_f32_16x16x4_f32 v[188:191], v179, v123, v[188:191]
	s_waitcnt lgkmcnt(0)
	v_mfma_f32_16x16x4_f32 v[52:55], v180, v124, v[52:55]
	v_mfma_f32_16x16x4_f32 v[188:191], v184, v128, v[188:191]
	v_mfma_f32_16x16x4_f32 v[52:55], v181, v125, v[52:55]
	v_mfma_f32_16x16x4_f32 v[188:191], v185, v129, v[188:191]
	v_mfma_f32_16x16x4_f32 v[52:55], v182, v126, v[52:55]
	v_mfma_f32_16x16x4_f32 v[188:191], v186, v130, v[188:191]
	v_mfma_f32_16x16x4_f32 v[52:55], v183, v127, v[52:55]
	v_mfma_f32_16x16x4_f32 v[188:191], v187, v131, v[188:191]
	s_nop 9
	s_nop 1
	v_add_f32_e32 v52, v52, v188
	v_add_f32_e32 v53, v53, v189
	v_add_f32_e32 v54, v54, v190
	v_add_f32_e32 v55, v55, v191
	v_fma_f32 v52, v87, v57, v52
	v_mul_f32_e32 v57, v52, v52
	v_fmamk_f32 v57, v57, 0xbdd2d3e8, v196
	v_mul_f32_e32 v57, v52, v57
	v_exp_f32_e32 v57, v57
	s_nop 0
	v_add_f32_e32 v57, 1.0, v57
	v_rcp_f32_e32 v57, v57
	s_nop 0
	v_mul_f32_e32 v52, v52, v57
	v_bfe_u32 v57, v52, 16, 1
	v_add3_u32 v52, v52, v57, s80
	global_store_short_d16_hi v[60:61], v52, off
	v_lshl_add_u64 v[60:61], v[0:1], 0, s[0:1]
	s_waitcnt vmcnt(11)
	v_lshlrev_b32_e32 v0, 16, v134
	v_fma_f32 v0, v87, v0, v53
	v_mul_f32_e32 v52, v0, v0
	v_fmamk_f32 v52, v52, 0xbdd2d3e8, v196
	v_mul_f32_e32 v52, v0, v52
	v_exp_f32_e32 v52, v52
	v_mov_b32_e32 v57, v1
	v_add_f32_e32 v52, 1.0, v52
	v_rcp_f32_e32 v52, v52
	s_nop 0
	v_mul_f32_e32 v0, v0, v52
	v_bfe_u32 v52, v0, 16, 1
	v_add3_u32 v0, v0, v52, s80
	v_lshlrev_b64 v[52:53], 10, v[60:61]
	v_lshl_add_u64 v[52:53], v[92:93], 0, v[52:53]
	global_store_short_d16_hi v[52:53], v0, off
	s_waitcnt vmcnt(11)
	v_lshlrev_b32_e32 v0, 16, v133
	v_fma_f32 v0, v87, v0, v54
	v_mul_f32_e32 v54, v0, v0
	v_fmamk_f32 v54, v54, 0xbdd2d3e8, v196
	v_mul_f32_e32 v54, v0, v54
	v_exp_f32_e32 v54, v54
	v_lshl_add_u64 v[52:53], v[58:59], 0, s[0:1]
	v_lshlrev_b64 v[52:53], 10, v[52:53]
	v_lshl_add_u64 v[52:53], v[92:93], 0, v[52:53]
	v_add_f32_e32 v54, 1.0, v54
	v_rcp_f32_e32 v54, v54
	s_nop 0
	v_mul_f32_e32 v0, v0, v54
	v_bfe_u32 v54, v0, 16, 1
	v_add3_u32 v0, v0, v54, s80
	global_store_short_d16_hi v[52:53], v0, off
	s_waitcnt vmcnt(11)
	v_lshlrev_b32_e32 v0, 16, v132
	v_fmac_f32_e32 v55, v87, v0
	v_mul_f32_e32 v0, v55, v55
	v_fmamk_f32 v0, v0, 0xbdd2d3e8, v196
	v_mul_f32_e32 v0, v55, v0
	v_exp_f32_e32 v0, v0
	v_lshl_add_u64 v[52:53], v[56:57], 0, s[0:1]
	v_lshlrev_b64 v[52:53], 10, v[52:53]
	v_lshl_add_u64 v[52:53], v[92:93], 0, v[52:53]
	v_add_f32_e32 v0, 1.0, v0
	v_rcp_f32_e32 v0, v0
	s_nop 0
	v_mul_f32_e32 v0, v55, v0
	v_bfe_u32 v54, v0, 16, 1
	v_add3_u32 v0, v0, v54, s80
	global_store_short_d16_hi v[52:53], v0, off
	s_cbranch_scc0 .LBB0_149
	s_add_i32 s9, s9, s33
	s_cmpk_gt_i32 s9, 0xfff
	s_cbranch_scc0 .LBB0_141
